# V^T LDS tile re-layout (single ds_read_b128 per PV fragment) also applied to the FoX and stick-breaking attention loops
# baseline (speedup 1.0000x reference)
; DI int otid() { int t = threadIdx.x; asm volatile("" : "+v"(t)); return t; }
; DI unsigned xb_xcc_id() { return (unsigned)__builtin_amdgcn_s_getreg((3 << 11) | 20) & 0xFu; }
;   constexpr int DQK = (MODE == 1) ? 96 : 64, NKS = DQK / 16, KST = DQK + 8;
;   constexpr int KCH = (MODE == 1) ? 3 : 2;
;   const int t = otid(), lane = t & 63, w = t >> 6, r = lane & 31, hh = lane >> 5;
;   bf16_t* Kl = smem;
;   bf16_t* Vl = smem + 2 * 64 * KST;
;   float* Fl = (float*)(Vl + 2 * 64 * VST);
;   int* s_item = (int*)(Fl + 128);
;   int* s_flag = s_item + 4;
;   const int total = NB * NH * 65;
;   const int lkey = t >> 2, lsub = t & 3;
;   constexpr float LOG2E = 1.44269504f;
;   const float c2 = (MODE == 1 ? 0.10206207f : 0.125f) * LOG2E;
;   const int myx = (int)(xb_xcc_id() & 7u);
;     ...
;     auto lstore = [&](const u32x4 (&rk)[KCH], const u32x4 (&rv)[2], const float rf, int buf) {
;       bf16_t* kd = Kl + buf * 64 * KST + lkey * KST + lsub * 8;
;       *(u32x4*)kd = rk[0]; *(u32x4*)(kd + 32) = rk[1];
;       if (MODE == 1) *(u32x4*)(kd + 64) = rk[KCH - 1];
;       bf16_t* vd = Vl + buf * 64 * VST + lkey * VST + lsub * 8;
;       u32x2 lo, hi;
;       lo[0] = rv[0][0]; lo[1] = rv[0][1]; hi[0] = rv[0][2]; hi[1] = rv[0][3];
;       *(u32x2*)vd = lo; *(u32x2*)(vd + 4) = hi;
;       lo[0] = rv[1][0]; lo[1] = rv[1][1]; hi[0] = rv[1][2]; hi[1] = rv[1][3];
;       *(u32x2*)(vd + 32) = lo; *(u32x2*)(vd + 36) = hi;
;       if (MODE == 2 && t < 64) Fl[buf * 64 + t] = -rf * LOG2E;
;     };
.LBB0_381:
	s_andn2_b64 vcc, exec, s[4:5]
	s_cbranch_vccnz .LBB0_491
	v_mov_b32_e32 v1, v172
	s_movk_i32 s1, 0x90
	v_lshlrev_b32_e32 v2, 3, v1
	v_and_b32_e32 v2, 24, v2
	v_ashrrev_i32_e32 v129, 2, v1
	v_lshlrev_b32_e32 v144, 1, v2
	v_mad_u64_u32 v[130:131], s[4:5], v129, s1, v[144:145]
	v_and_b32_e32 v5, 31, v1
	v_readlane_b32 s4, v228, 18
	v_and_b32_e32 v128, 63, v1
	v_ashrrev_i32_e32 v3, 6, v1
	v_bfe_u32 v4, v1, 5, 1
	v_cmp_eq_u32_e64 s[42:43], 0, v1
	v_cmp_gt_i32_e64 s[44:45], 64, v1
	v_lshlrev_b32_e32 v163, 2, v1
	v_mul_u32_u24_e32 v1, 0x48, v5
	v_readlane_b32 s5, v228, 19
	v_lshlrev_b32_e32 v162, 5, v3
	v_lshlrev_b32_e32 v164, 2, v3
	v_lshlrev_b32_e32 v1, 1, v1
	v_lshlrev_b32_e32 v165, 4, v4
	v_lshlrev_b32_e32 v3, 3, v5
	v_lshl_add_u64 v[132:133], s[4:5], 0, v[144:145]
	v_readlane_b32 s4, v228, 23
	v_lshlrev_b32_e32 v0, 3, v4
	v_lshlrev_b32_e32 v6, 3, v129
	v_add_u32_e32 v166, v1, v165
	v_mul_i32_i24_e32 v167, -4, v4
	v_sub_u32_e32 v1, v1, v3
	v_lshlrev_b32_e32 v4, 2, v4
	v_readlane_b32 s5, v228, 24
	s_getreg_b32 s14, hwreg(HW_REG_XCC_ID, 0, 4)
	s_mov_b32 s15, 0
	v_sub_u32_e32 v131, v130, v6
	v_lshrrev_b32_e32 v230, 2, v172
	v_mul_u32_u24_e32 v131, 0x90, v230
	v_bfe_u32 v230, v172, 1, 1
	v_lshl_add_u32 v131, v230, 5, v131
	v_and_b32_e32 v230, 1, v172
	v_lshl_add_u32 v131, v230, 3, v131
	v_cmp_eq_u32_e64 s[46:47], 0, v128
	v_add_u32_e32 v168, v1, v0
	v_and_b32_e32 v230, 31, v172
	v_mul_u32_u24_e32 v168, 0x90, v230
	v_bfe_u32 v230, v172, 5, 1
	v_lshl_add_u32 v168, v230, 4, v168
	v_or_b32_e32 v169, 0x2000, v5
	v_lshl_add_u64 v[134:135], s[4:5], 0, v[144:145]
	v_lshlrev_b32_e32 v144, 1, v0
	v_lshlrev_b32_e32 v136, 1, v2
	v_lshlrev_b32_e32 v138, 1, v4
	s_mov_b32 s24, 0xf800000
	s_branch .LBB0_384

; DI float bf2f(short s) { return __uint_as_float(((unsigned)(unsigned short)s) << 16); }
;     ...
;     __syncthreads();
;     const int enc = s_item[0]; qx = s_item[1];
;     if (enc < 0) break;
;     const int xx_ = enc & 7, idx = enc >> 3;
;     const int qt = 64 - idx % 65, bh = (idx / 65) * 8 + xx_, b = bh >> 4, hd = bh & 15;
;     const int q0 = qt * 128;
;     const int posq = q0 + w * 32 + r;
;     const bool qvalid = posq < L;
;     const int pq = qvalid ? posq : L - 1;
;     bf16_t* qptr = aa.q + (size_t)(b * L + pq) * aa.ldq + hd * aa.hs;
;     bf16x8 qf[NKS];
; #pragma unroll
;     for (int ks = 0; ks < NKS; ++ks) qf[ks] = *(const bf16x8*)(qptr + ks * 16 + 8 * hh);
;     if (MODE == 1) {
; #pragma unroll
;       for (int j = 0; j < 8; j += 2) {
;         float o1[2], o2[2];
; #pragma unroll
;         for (int e = 0; e < 2; ++e) {
;           const int i = 8 * hh + j + e;
;           const float inv = fexp2(-(float)i * 0.83048202f);
;           const float ang = (float)pq * inv;
;           const float n = rintf(ang * 0.15915494f);
;           float rr = fmaf(-n, 6.2831855f, ang); rr = fmaf(-n, -1.7484555e-7f, rr);
;           const float cs = __cosf(rr), sn = __sinf(rr);
;           const float x1 = bf2f(qf[NKS - 2][j + e]), x2 = bf2f(qf[NKS - 1][j + e]);
;           o1[e] = x1 * cs - x2 * sn; o2[e] = x2 * cs + x1 * sn;
;         }
;         const unsigned p1 = pk_bf16(o1[0], o1[1]), p2 = pk_bf16(o2[0], o2[1]);
;         qf[NKS - 2][j] = (short)(p1 & 0xffff); qf[NKS - 2][j + 1] = (short)(p1 >> 16);
;         qf[NKS - 1][j] = (short)(p2 & 0xffff); qf[NKS - 1][j + 1] = (short)(p2 >> 16);
;       }
;     }
;     float Bq = 0.f;
;     if (MODE == 2) {
;       float qq = 0.f;
; #pragma unroll
;       for (int ks = 0; ks < NKS; ++ks)
; #pragma unroll
;         for (int j = 0; j < 8; ++j) { const float x = bf2f(qf[ks][j]); qq += x * x; }
;       qq += __shfl_xor(qq, 32);
;       Bq = sqrtf(qq) * sqrtf(__uint_as_float(aa.kmax[bh])) * (c2 * 1.02f);
;     }
;     ...
;     auto gload = [&](u32x4 (&rk)[KCH], u32x4 (&rv)[2], float& rf, int ktile) {
;       int kp = ktile * 64 + lkey; kp = kp < L ? kp : L - 1;
;       const size_t mk = (size_t)(b * L + kp);
;       const bf16_t* ks_ = aa.k + mk * D + hd * 64 + lsub * 8;
;       rk[0] = *(const u32x4*)ks_; __builtin_amdgcn_sched_barrier(0);
;       rk[1] = *(const u32x4*)(ks_ + 32); __builtin_amdgcn_sched_barrier(0);
.LBB0_395:
	s_or_b64 exec, exec, s[4:5]
	s_waitcnt lgkmcnt(0)
	s_barrier
	ds_read_b64 v[0:1], v145 offset:36352
	s_waitcnt lgkmcnt(0)
	v_readfirstlane_b32 s1, v0
	s_cmp_lt_i32 s1, 0
	v_readfirstlane_b32 s15, v1
	s_cbranch_scc1 .LBB0_440
	s_lshr_b32 s5, s1, 3
	s_mul_hi_u32 s6, s5, 0x3f03f04
	s_mulk_i32 s6, 0x41
	s_sub_i32 s5, s5, s6
	s_mul_hi_u32 s6, s1, 0xfc0fc0fd
	s_and_b32 s4, s1, 7
	s_lshr_b32 s1, s6, 6
	s_and_b32 s1, s1, 0x3fffff8
	s_or_b32 s1, s1, s4
	s_lshl_b32 s4, s5, 7
	v_subrev_u32_e32 v2, s4, v162
	s_lshr_b32 s10, s6, 10
	v_add_u32_e32 v139, v2, v169
	v_min_i32_e32 v0, 0x200f, v139
	s_mulk_i32 s10, 0x2010
	v_add_u32_e32 v0, s10, v0
	v_ashrrev_i32_e32 v1, 31, v0
	s_lshl_b32 s5, s1, 6
	v_lshlrev_b64 v[0:1], 11, v[0:1]
	s_and_b32 s6, s5, 0x3c0
	v_lshl_add_u64 v[0:1], s[68:69], 0, v[0:1]
	s_lshl_b32 s18, s6, 1
	v_lshl_add_u64 v[140:141], v[0:1], 0, s[18:19]
	v_lshl_add_u64 v[0:1], v[140:141], 0, v[144:145]
	global_load_dwordx4 v[64:67], v[0:1], off
	global_load_dwordx4 v[68:71], v[0:1], off offset:32
	global_load_dwordx4 v[72:75], v[0:1], off offset:64
	global_load_dwordx4 v[76:79], v[0:1], off offset:96
	s_lshl_b32 s6, s1, 2
	s_sub_i32 s4, 0x2040, s4
	s_lshr_b32 s4, s4, 6
	s_min_u32 s11, s4, 0x80
	v_readlane_b32 s12, v228, 23
	v_readlane_b32 s13, v228, 24
	v_mov_b32_e32 v137, v145
	s_waitcnt vmcnt(3)
	v_and_b32_e32 v1, 0xffff0000, v64
	v_lshlrev_b32_e32 v0, 16, v64
	v_mul_f32_e32 v3, v1, v1
	v_fmac_f32_e32 v3, v0, v0
	v_lshlrev_b32_e32 v0, 16, v65
	v_fmac_f32_e32 v3, v0, v0
	v_and_b32_e32 v0, 0xffff0000, v65
	v_fmac_f32_e32 v3, v0, v0
	v_lshlrev_b32_e32 v0, 16, v66
	v_fmac_f32_e32 v3, v0, v0
	v_and_b32_e32 v0, 0xffff0000, v66
	v_fmac_f32_e32 v3, v0, v0
	v_lshlrev_b32_e32 v0, 16, v67
	v_fmac_f32_e32 v3, v0, v0
	v_and_b32_e32 v0, 0xffff0000, v67
	v_fmac_f32_e32 v3, v0, v0
	s_waitcnt vmcnt(2)
	v_lshlrev_b32_e32 v0, 16, v68
	v_fmac_f32_e32 v3, v0, v0
	v_and_b32_e32 v0, 0xffff0000, v68
	v_fmac_f32_e32 v3, v0, v0
	v_lshlrev_b32_e32 v0, 16, v69
	v_fmac_f32_e32 v3, v0, v0
	v_and_b32_e32 v0, 0xffff0000, v69
	v_fmac_f32_e32 v3, v0, v0
	v_lshlrev_b32_e32 v0, 16, v70
	v_fmac_f32_e32 v3, v0, v0
	v_and_b32_e32 v0, 0xffff0000, v70
	v_fmac_f32_e32 v3, v0, v0
	v_lshlrev_b32_e32 v0, 16, v71
	v_fmac_f32_e32 v3, v0, v0
	v_and_b32_e32 v0, 0xffff0000, v71
	v_fmac_f32_e32 v3, v0, v0
	s_waitcnt vmcnt(1)
	v_lshlrev_b32_e32 v0, 16, v72
	v_fmac_f32_e32 v3, v0, v0
	v_and_b32_e32 v0, 0xffff0000, v72
	v_fmac_f32_e32 v3, v0, v0
	v_lshlrev_b32_e32 v0, 16, v73
	v_fmac_f32_e32 v3, v0, v0
	v_and_b32_e32 v0, 0xffff0000, v73
	v_fmac_f32_e32 v3, v0, v0
	v_lshlrev_b32_e32 v0, 16, v74
	v_fmac_f32_e32 v3, v0, v0
	v_and_b32_e32 v0, 0xffff0000, v74
	v_fmac_f32_e32 v3, v0, v0
	v_lshlrev_b32_e32 v0, 16, v75
	v_fmac_f32_e32 v3, v0, v0
	v_and_b32_e32 v0, 0xffff0000, v75
	v_fmac_f32_e32 v3, v0, v0
	s_waitcnt vmcnt(0)
	v_lshlrev_b32_e32 v0, 16, v76
	v_fmac_f32_e32 v3, v0, v0
	v_and_b32_e32 v0, 0xffff0000, v76
	v_fmac_f32_e32 v3, v0, v0
	v_lshlrev_b32_e32 v0, 16, v77
	v_fmac_f32_e32 v3, v0, v0
	v_and_b32_e32 v0, 0xffff0000, v77
	v_fmac_f32_e32 v3, v0, v0
	v_lshlrev_b32_e32 v0, 16, v78
	v_fmac_f32_e32 v3, v0, v0
	v_and_b32_e32 v0, 0xffff0000, v78
	v_fmac_f32_e32 v3, v0, v0
	v_lshlrev_b32_e32 v0, 16, v79
	v_fmac_f32_e32 v3, v0, v0
	v_and_b32_e32 v0, 0xffff0000, v79
	v_and_b32_e32 v1, 64, v182
	v_fmac_f32_e32 v3, v0, v0
	v_xor_b32_e32 v0, 32, v182
	v_add_u32_e32 v1, 64, v1
	v_cmp_lt_i32_e32 vcc, v0, v1
	s_nop 1
	v_cndmask_b32_e32 v0, v182, v0, vcc
	v_lshlrev_b32_e32 v170, 2, v0
	v_mov_b32_e32 v0, s6
	global_load_dword v4, v0, s[70:71] offset:64
	v_add_u32_e32 v0, s5, v129
	v_mad_i64_i32 v[142:143], s[4:5], v0, s27, v[132:133]
	s_lshl_b32 s4, s11, 6
	s_nop 0
	v_add_u32_e32 v0, s4, v129
	v_min_i32_e32 v0, 0x200f, v0
	v_add_u32_e32 v0, s10, v0
	v_ashrrev_i32_e32 v1, 31, v0
	v_lshlrev_b64 v[0:1], 11, v[0:1]
	v_lshl_add_u64 v[0:1], s[12:13], 0, v[0:1]
	v_lshl_add_u64 v[0:1], v[0:1], 0, s[18:19]
	v_lshl_add_u64 v[0:1], v[0:1], 0, v[136:137]
	global_load_dwordx4 v[80:83], v[0:1], off
	ds_bpermute_b32 v5, v170, v3
	global_load_dwordx4 v[84:87], v[0:1], off offset:64
	s_lshl_b32 s6, s11, 7
	s_mov_b32 s7, s19
	v_lshl_add_u64 v[0:1], v[142:143], 0, s[6:7]
	global_load_dwordx4 v[88:91], v[0:1], off
	global_load_dwordx4 v[92:95], v[0:1], off offset:64
	s_mul_hi_u32 s5, s1, 0x8100
	s_mul_i32 s1, s1, 0x8100
	s_add_u32 s6, s62, s1
	s_addc_u32 s7, s63, s5
	s_lshl_b32 s1, s11, 8
	s_add_u32 s8, s6, s1
	s_addc_u32 s9, s7, 0
	v_lshlrev_b32_e32 v0, 2, v128
	global_load_dword v187, v0, s[8:9]
	s_sub_i32 s4, s4, 64
	v_add_u32_e32 v1, s4, v129
	v_min_i32_e32 v1, 0x200f, v1
	v_add_u32_e32 v6, s10, v1
	v_ashrrev_i32_e32 v7, 31, v6
	v_lshlrev_b64 v[6:7], 11, v[6:7]
	v_lshl_add_u64 v[6:7], s[12:13], 0, v[6:7]
	v_lshl_add_u64 v[6:7], v[6:7], 0, s[18:19]
	v_lshl_add_u64 v[6:7], v[6:7], 0, v[136:137]
	global_load_dwordx4 v[96:99], v[6:7], off
	global_load_dwordx4 v[100:103], v[6:7], off offset:64
	s_mov_b32 s5, s19
	v_lshl_add_u64 v[6:7], s[4:5], 1, v[142:143]
	global_load_dwordx4 v[104:107], v[6:7], off
	global_load_dwordx4 v[108:111], v[6:7], off offset:64
	s_lshl_b64 s[4:5], s[4:5], 2
	s_add_u32 s4, s6, s4
	s_addc_u32 s5, s7, s5
	global_load_dword v188, v0, s[4:5]
	v_add_u32_e32 v137, 0x4800, v131
	v_add_u32_e32 v171, 0x4840, v131
	s_waitcnt vmcnt(9)
	ds_write_b128 v130, v[80:83]
	s_waitcnt vmcnt(8)
	ds_write_b128 v130, v[84:87] offset:64
	s_waitcnt vmcnt(7)
	ds_write2_b64 v137, v[88:89], v[90:91] offset1:2
	s_waitcnt vmcnt(6)
	ds_write2_b64 v171, v[92:93], v[94:95] offset1:2
	s_and_saveexec_b64 s[4:5], s[44:45]
	s_cbranch_execz .LBB0_398
	s_waitcnt vmcnt(5)
	v_mul_f32_e32 v1, 0xbfb8aa3b, v187
	ds_write_b32 v163, v1 offset:35840

;     ...
;       if (MODE == 2) { const float fl = aa.Fh[(size_t)bh * LP + (kt > 0 ? kt * 64 - 1 : 0)]; __builtin_amdgcn_sched_barrier(0); nfnext = (kt > 0) ? -fl * LOG2E : 0.f; }
;       { const int kpre = kt > 1 ? kt - 2 : 0; if (PAR == 0) gload(rkA, rvA, rfA, kpre); else gload(rkB, rvB, rfB, kpre); }
;       if (kt * 64 <= wqmax && dry < 2) {
;         const bf16_t* Kb = Kl + buf * 64 * KST; const bf16_t* Vb = Vl + buf * 64 * VST;
;         f32x16 s[2];
; #pragma unroll
;         for (int i = 0; i < 16; ++i) { s[0][i] = 0.f; s[1][i] = 0.f; }
;         if (MODE == 0) {
; #pragma unroll
;           for (int ks = 0; ks < NKS; ++ks) {
;             const bf16x8 a0 = *(const bf16x8*)(Kb + r * KST + ks * 16 + 8 * hh);
;             const bf16x8 a1 = *(const bf16x8*)(Kb + (32 + r) * KST + ks * 16 + 8 * hh);
;             s[0] = MFMA32(a0, qf[ks], s[0]);
;             s[1] = MFMA32(a1, qf[ks], s[1]);
;           }
;         } else {
;           bf16x8 kf0[NKS], kf1[NKS];
; #pragma unroll
;           for (int ks = 0; ks < NKS; ++ks) kf0[ks] = *(const bf16x8*)(Kb + r * KST + ks * 16 + 8 * hh);
; #pragma unroll
;           for (int ks = 0; ks < NKS; ++ks) kf1[ks] = *(const bf16x8*)(Kb + (32 + r) * KST + ks * 16 + 8 * hh);
;           __builtin_amdgcn_sched_barrier(0);
; #pragma unroll
;           for (int ks = 0; ks < NKS; ++ks) s[0] = MFMA32(kf0[ks], qf[ks], s[0]);
; #pragma unroll
;           for (int ks = 0; ks < NKS; ++ks) s[1] = MFMA32(kf1[ks], qf[ks], s[1]);
;           __builtin_amdgcn_sched_barrier(0);
;         }
;         const int kbase = kt * 64 + 4 * hh;
;         u32x4 vfr[2][2];
;         auto ldv = [&](int j) {
; #pragma unroll
;           for (int st = 0; st < 2; ++st)
; #pragma unroll
;             for (int dt = 0; dt < 2; ++dt) {
;               const bf16_t* vp = Vb + (dt * 32 + r) * VST + j * 32 + 16 * st + 4 * hh;
;               const u32x2 lo = *(const u32x2*)vp, hi = *(const u32x2*)(vp + 8);
;               vfr[st][dt][0] = lo[0]; vfr[st][dt][1] = lo[1]; vfr[st][dt][2] = hi[0]; vfr[st][dt][3] = hi[1];
;             }
;           __builtin_amdgcn_sched_barrier(0);
;         };
;     ...
;           const bool diag = kt * 64 + 63 > q0 + w * 32;
;           const int dq = posq - kbase;
; #pragma unroll
;           for (int j = 0; j < 2; ++j) {
;             ldv(j);
;             if (MODE == 2) {
; #pragma unroll
;               for (int g = 0; g < 4; ++g) {
.LBB0_405:
	s_lshl_b32 s1, s11, 6
	s_add_i32 s8, s1, -1
	s_cmp_gt_i32 s11, 0
	s_cselect_b64 s[52:53], -1, 0
	s_and_b64 s[4:5], s[52:53], exec
	s_cselect_b32 s18, s8, 0
	s_lshl_b64 s[4:5], s[18:19], 2
	s_add_u32 s4, s6, s4
	s_addc_u32 s5, s7, s5
	global_load_dword v156, v145, s[4:5]
	s_max_i32 s4, s11, 2
	s_lshl_b32 s4, s4, 6
	s_addk_i32 s4, 0xff80
	v_add_u32_e32 v32, s4, v129
	v_min_i32_e32 v32, 0x200f, v32
	v_add_u32_e32 v32, s10, v32
	v_ashrrev_i32_e32 v33, 31, v32
	v_lshlrev_b64 v[32:33], 11, v[32:33]
	v_lshl_add_u64 v[32:33], v[152:153], 0, v[32:33]
	global_load_dwordx4 v[80:83], v[32:33], off
	global_load_dwordx4 v[84:87], v[32:33], off offset:64
	s_ashr_i32 s5, s4, 31
	v_lshl_add_u64 v[32:33], s[4:5], 1, v[142:143]
	global_load_dwordx4 v[88:91], v[32:33], off
	global_load_dwordx4 v[92:95], v[32:33], off offset:64
	v_lshl_add_u64 v[32:33], s[4:5], 2, v[154:155]
	global_load_dword v187, v[32:33], off
	v_cmp_le_i32_e32 vcc, s1, v189
	s_and_saveexec_b64 s[4:5], vcc
	s_cbranch_execz .LBB0_417
	ds_read_b128 v[32:35], v166
	ds_read_b128 v[36:39], v166 offset:32
	ds_read_b128 v[40:43], v166 offset:64
	ds_read_b128 v[44:47], v166 offset:96
	ds_read_b128 v[112:115], v166 offset:4608
	ds_read_b128 v[116:119], v166 offset:4640
	ds_read_b128 v[120:123], v166 offset:4672
	ds_read_b128 v[124:127], v166 offset:4704
	s_waitcnt lgkmcnt(7)
	v_mfma_f32_32x32x16_bf16 v[48:63], v[32:35], v[64:67], 0
	s_waitcnt lgkmcnt(6)
	v_mfma_f32_32x32x16_bf16 v[48:63], v[36:39], v[68:71], v[48:63]
	s_waitcnt lgkmcnt(5)
	v_mfma_f32_32x32x16_bf16 v[48:63], v[40:43], v[72:75], v[48:63]
	s_waitcnt lgkmcnt(4)
	v_mfma_f32_32x32x16_bf16 v[48:63], v[44:47], v[76:79], v[48:63]
	s_waitcnt lgkmcnt(3)
	v_mfma_f32_32x32x16_bf16 v[32:47], v[112:115], v[64:67], 0
	s_waitcnt lgkmcnt(2)
	v_mfma_f32_32x32x16_bf16 v[32:47], v[116:119], v[68:71], v[32:47]
	s_waitcnt lgkmcnt(1)
	v_mfma_f32_32x32x16_bf16 v[32:47], v[120:123], v[72:75], v[32:47]
	s_waitcnt lgkmcnt(0)
	v_mfma_f32_32x32x16_bf16 v[32:47], v[124:127], v[76:79], v[32:47]
	v_subrev_u32_e32 v112, s1, v167
	v_add_u32_e32 v194, 0x4800, v168
	v_add_u32_e32 v195, 0x5800, v168
	v_add_u32_e32 v192, v112, v139
	ds_read_b128 v[124:127], v168 offset:18432
	ds_read_b128 v[112:115], v168 offset:18464
	ds_read_b128 v[120:123], v168 offset:23040
	ds_read_b128 v[116:119], v168 offset:23072
	v_cmp_gt_i32_e64 s[54:55], s1, v190
	ds_read_b128 v[196:199], v165 offset:35840
	ds_read_b128 v[200:203], v165 offset:35872
	s_waitcnt lgkmcnt(1)
	v_pk_fma_f32 v[160:161], v[48:49], s[36:37], v[196:197] op_sel_hi:[1,0,1]
	v_pk_fma_f32 v[158:159], v[50:51], s[36:37], v[198:199] op_sel_hi:[1,0,1]
	ds_read_b128 v[196:199], v165 offset:35904
	s_waitcnt lgkmcnt(1)
	v_pk_fma_f32 v[50:51], v[52:53], s[36:37], v[200:201] op_sel_hi:[1,0,1]
	v_pk_fma_f32 v[48:49], v[54:55], s[36:37], v[202:203] op_sel_hi:[1,0,1]
	s_waitcnt lgkmcnt(0)
	v_pk_fma_f32 v[54:55], v[56:57], s[36:37], v[196:197] op_sel_hi:[1,0,1]
	v_pk_fma_f32 v[52:53], v[58:59], s[36:37], v[198:199] op_sel_hi:[1,0,1]
	ds_read_b128 v[56:59], v165 offset:35936
	s_waitcnt lgkmcnt(0)
	v_pk_fma_f32 v[56:57], v[60:61], s[36:37], v[56:57] op_sel_hi:[1,0,1]
	v_pk_fma_f32 v[58:59], v[62:63], s[36:37], v[58:59] op_sel_hi:[1,0,1]
	s_and_saveexec_b64 s[8:9], s[54:55]
	s_cbranch_execz .LBB0_408
	v_cmp_lt_i32_e32 vcc, -1, v192
	s_nop 1
	v_cndmask_b32_e32 v160, v185, v160, vcc
	v_cmp_lt_i32_e32 vcc, 0, v192
	s_nop 1
	v_cndmask_b32_e32 v161, v185, v161, vcc
	v_cmp_lt_i32_e32 vcc, 1, v192
	s_nop 1
	v_cndmask_b32_e32 v158, v185, v158, vcc
	v_cmp_lt_i32_e32 vcc, 2, v192
	s_nop 1
	v_cndmask_b32_e32 v159, v185, v159, vcc
	v_cmp_lt_i32_e32 vcc, 7, v192
	s_nop 1
	v_cndmask_b32_e32 v50, v185, v50, vcc
	v_cmp_lt_i32_e32 vcc, 8, v192
	s_nop 1
	v_cndmask_b32_e32 v51, v185, v51, vcc
	v_cmp_lt_i32_e32 vcc, 9, v192
	s_nop 1
	v_cndmask_b32_e32 v48, v185, v48, vcc
	v_cmp_lt_i32_e32 vcc, 10, v192
	s_nop 1
	v_cndmask_b32_e32 v49, v185, v49, vcc
	v_cmp_lt_i32_e32 vcc, 15, v192
	s_nop 1
	v_cndmask_b32_e32 v54, v185, v54, vcc
	v_cmp_lt_i32_e32 vcc, 16, v192
	s_nop 1
	v_cndmask_b32_e32 v55, v185, v55, vcc
	v_cmp_lt_i32_e32 vcc, 17, v192
	s_nop 1
	v_cndmask_b32_e32 v52, v185, v52, vcc
	v_cmp_lt_i32_e32 vcc, 18, v192
	s_nop 1
	v_cndmask_b32_e32 v53, v185, v53, vcc
	v_cmp_lt_i32_e32 vcc, 23, v192
	s_nop 1
	v_cndmask_b32_e32 v56, v185, v56, vcc
	v_cmp_lt_i32_e32 vcc, 24, v192
	s_nop 1
	v_cndmask_b32_e32 v57, v185, v57, vcc
	v_cmp_lt_i32_e32 vcc, 25, v192
	s_nop 1
	v_cndmask_b32_e32 v58, v185, v58, vcc
	v_cmp_lt_i32_e32 vcc, 26, v192
	s_nop 1
	v_cndmask_b32_e32 v59, v185, v59, vcc

; DI float fexp2(float x) { return __builtin_amdgcn_exp2f(x); }
;     ...
;           for (int j = 0; j < 2; ++j) {
;             ldv(j);
;             if (MODE == 2) {
; #pragma unroll
;               for (int g = 0; g < 4; ++g) {
;                 const f32x4 nf = *(const f32x4*)(Fl + buf * 64 + j * 32 + 8 * g + 4 * hh);
; #pragma unroll
;                 for (int e = 0; e < 4; ++e) s[j][4 * g + e] = fmaf(s[j][4 * g + e], c2, nf[e]);
;               }
;             }
;             if (diag) {
;               asm volatile("" ::: "memory");
; #pragma unroll
;               for (int i = 0; i < 16; ++i) s[j][i] = (j * 32 + 8 * (i >> 2) + (i & 3)) <= dq ? s[j][i] : -INFINITY;
;             }
;             float mt = fmaxf(s[j][0], s[j][1]);
; #pragma unroll
;             for (int i = 2; i < 16; ++i) mt = fmaxf(mt, s[j][i]);
;             mt = fmaxf(mt, __shfl_xor(mt, 32));
;             if (MODE == 1) mt *= c2;
;             const float cand = fmaxf(mrun, mt);
;             if (__any(cand > mrun + 8.f)) {
;               const float alpha = fexp2(mrun - cand);
;               mrun = cand; lsum *= alpha;
; #pragma unroll
;               for (int i = 0; i < 16; ++i) { oacc[0][i] *= alpha; oacc[1][i] *= alpha; }
;             }
;             const float nm = -mrun;
; #pragma unroll
;             for (int i = 0; i < 16; ++i) {
;               const float p = (MODE == 1) ? fexp2(fmaf(s[j][i], c2, nm)) : fexp2(s[j][i] + nm);
;               lsum += p; s[j][i] = p;
;             }
;             pvm(j);
.LBB0_411:
	v_sub_f32_e32 v48, v48, v193
	v_exp_f32_e32 v201, v48
	v_sub_f32_e32 v48, v49, v193
	v_sub_f32_e32 v60, v160, v193
	v_exp_f32_e32 v202, v48
	v_sub_f32_e32 v48, v54, v193
	v_exp_f32_e32 v160, v60
	v_sub_f32_e32 v60, v161, v193
	v_exp_f32_e32 v203, v48
	v_sub_f32_e32 v48, v55, v193
	v_exp_f32_e32 v196, v60
	v_sub_f32_e32 v60, v158, v193
	v_sub_f32_e32 v50, v50, v193
	v_exp_f32_e32 v204, v48
	v_sub_f32_e32 v48, v52, v193
	v_exp_f32_e32 v197, v60
	v_sub_f32_e32 v60, v159, v193
	v_exp_f32_e32 v199, v50
	v_sub_f32_e32 v50, v51, v193
	v_exp_f32_e32 v205, v48
	v_sub_f32_e32 v48, v53, v193
	v_exp_f32_e32 v198, v60
	v_exp_f32_e32 v200, v50
	v_exp_f32_e32 v206, v48
	v_sub_f32_e32 v48, v56, v193
	v_exp_f32_e32 v157, v48
	v_sub_f32_e32 v48, v57, v193
	v_exp_f32_e32 v158, v48
	v_sub_f32_e32 v48, v58, v193
	v_exp_f32_e32 v159, v48
	v_sub_f32_e32 v48, v59, v193
	v_exp_f32_e32 v161, v48
	v_cvt_pk_bf16_f32 v48, v160, v196
	v_cvt_pk_bf16_f32 v49, v197, v198
	v_cvt_pk_bf16_f32 v50, v199, v200
	v_cvt_pk_bf16_f32 v51, v201, v202
	s_nop 1
	v_mfma_f32_32x32x16_bf16 v[16:31], v[124:127], v[48:51], v[16:31]
	v_mfma_f32_32x32x16_bf16 v[0:15], v[120:123], v[48:51], v[0:15]
	v_cvt_pk_bf16_f32 v48, v203, v204
	v_cvt_pk_bf16_f32 v49, v205, v206
	v_cvt_pk_bf16_f32 v50, v157, v158
	v_cvt_pk_bf16_f32 v51, v159, v161
	s_nop 1
	v_mfma_f32_32x32x16_bf16 v[16:31], v[112:115], v[48:51], v[16:31]
	v_mfma_f32_32x32x16_bf16 v[0:15], v[116:119], v[48:51], v[0:15]
	ds_read_b128 v[60:63], v168 offset:18496
	ds_read_b128 v[52:55], v168 offset:18528
	ds_read_b128 v[56:59], v168 offset:23104
	ds_read_b128 v[48:51], v168 offset:23136
	ds_read_b128 v[114:117], v165 offset:35968
	ds_read_b128 v[118:121], v165 offset:36000
	s_waitcnt lgkmcnt(1)
	v_pk_fma_f32 v[112:113], v[34:35], s[36:37], v[116:117] op_sel_hi:[1,0,1]
	s_waitcnt lgkmcnt(0)
	v_pk_fma_f32 v[36:37], v[36:37], s[36:37], v[118:119] op_sel_hi:[1,0,1]
	ds_read_b128 v[116:119], v165 offset:36032
	v_pk_fma_f32 v[114:115], v[32:33], s[36:37], v[114:115] op_sel_hi:[1,0,1]
	v_pk_fma_f32 v[34:35], v[38:39], s[36:37], v[120:121] op_sel_hi:[1,0,1]
	s_waitcnt lgkmcnt(0)
	v_pk_fma_f32 v[40:41], v[40:41], s[36:37], v[116:117] op_sel_hi:[1,0,1]
	v_pk_fma_f32 v[32:33], v[42:43], s[36:37], v[118:119] op_sel_hi:[1,0,1]
	ds_read_b128 v[116:119], v165 offset:36064
	s_waitcnt lgkmcnt(0)
	v_pk_fma_f32 v[42:43], v[44:45], s[36:37], v[116:117] op_sel_hi:[1,0,1]
	v_pk_fma_f32 v[38:39], v[46:47], s[36:37], v[118:119] op_sel_hi:[1,0,1]
	s_and_saveexec_b64 s[8:9], s[54:55]
	s_cbranch_execz .LBB0_413
	v_cmp_lt_i32_e32 vcc, 31, v192
	s_nop 1
	v_cndmask_b32_e32 v114, v185, v114, vcc
	v_cmp_lt_i32_e32 vcc, 32, v192
	s_nop 1
	v_cndmask_b32_e32 v115, v185, v115, vcc
	v_cmp_lt_i32_e32 vcc, 33, v192
	s_nop 1
	v_cndmask_b32_e32 v112, v185, v112, vcc
	v_cmp_lt_i32_e32 vcc, 34, v192
	s_nop 1
	v_cndmask_b32_e32 v113, v185, v113, vcc
	v_cmp_lt_i32_e32 vcc, 39, v192
	s_nop 1
	v_cndmask_b32_e32 v36, v185, v36, vcc
	v_cmp_lt_i32_e32 vcc, 40, v192
	s_nop 1
	v_cndmask_b32_e32 v37, v185, v37, vcc
	v_cmp_lt_i32_e32 vcc, 41, v192
	s_nop 1
	v_cndmask_b32_e32 v34, v185, v34, vcc
	v_cmp_lt_i32_e32 vcc, 42, v192
	s_nop 1
	v_cndmask_b32_e32 v35, v185, v35, vcc
	v_cmp_lt_i32_e32 vcc, 47, v192
	s_nop 1
	v_cndmask_b32_e32 v40, v185, v40, vcc
	v_cmp_lt_i32_e32 vcc, 48, v192
	s_nop 1
	v_cndmask_b32_e32 v41, v185, v41, vcc
	v_cmp_lt_i32_e32 vcc, 49, v192
	s_nop 1
	v_cndmask_b32_e32 v32, v185, v32, vcc
	v_cmp_lt_i32_e32 vcc, 50, v192
	s_nop 1
	v_cndmask_b32_e32 v33, v185, v33, vcc
	v_cmp_lt_i32_e32 vcc, 55, v192
	s_nop 1
	v_cndmask_b32_e32 v42, v185, v42, vcc
	v_cmp_lt_i32_e32 vcc, 56, v192
	s_nop 1
	v_cndmask_b32_e32 v43, v185, v43, vcc
	v_cmp_lt_i32_e32 vcc, 57, v192
	s_nop 1
	v_cndmask_b32_e32 v38, v185, v38, vcc
	v_cmp_lt_i32_e32 vcc, 58, v192
	s_nop 1
	v_cndmask_b32_e32 v39, v185, v39, vcc

;     ...
;     auto lstore = [&](const u32x4 (&rk)[KCH], const u32x4 (&rv)[2], const float rf, int buf) {
;       bf16_t* kd = Kl + buf * 64 * KST + lkey * KST + lsub * 8;
;       *(u32x4*)kd = rk[0]; *(u32x4*)(kd + 32) = rk[1];
;       if (MODE == 1) *(u32x4*)(kd + 64) = rk[KCH - 1];
;       bf16_t* vd = Vl + buf * 64 * VST + lkey * VST + lsub * 8;
;       u32x2 lo, hi;
;       lo[0] = rv[0][0]; lo[1] = rv[0][1]; hi[0] = rv[0][2]; hi[1] = rv[0][3];
;       *(u32x2*)vd = lo; *(u32x2*)(vd + 4) = hi;
;       lo[0] = rv[1][0]; lo[1] = rv[1][1]; hi[0] = rv[1][2]; hi[1] = rv[1][3];
;       *(u32x2*)(vd + 32) = lo; *(u32x2*)(vd + 36) = hi;
;       if (MODE == 2 && t < 64) Fl[buf * 64 + t] = -rf * LOG2E;
;     };
.LBB0_417:
	s_or_b64 exec, exec, s[4:5]
	v_add_u32_e32 v32, 0x9000, v131
	s_waitcnt vmcnt(10)
	ds_write_b128 v130, v[96:99] offset:9216
	s_waitcnt vmcnt(9)
	ds_write_b128 v130, v[100:103] offset:9280
	s_waitcnt vmcnt(8)
	ds_write2_b64 v32, v[104:105], v[106:107] offset1:2
	v_add_u32_e32 v32, 0x9040, v131
	s_waitcnt vmcnt(7)
	ds_write2_b64 v32, v[108:109], v[110:111] offset1:2
	s_and_saveexec_b64 s[4:5], s[44:45]
	s_cbranch_execz .LBB0_419
	s_waitcnt vmcnt(6)
	v_mul_f32_e32 v32, 0xbfb8aa3b, v188
	ds_write_b32 v163, v32 offset:36096

;     ...
;       if (MODE != 1) {
;         const int dn = (MODE == 0) ? ((!qvalid) || (Rrun < -120.f)) : ((!qvalid) || (Bq + nfnext < mrun - 150.f));
;         const int wd = __all(dn) ? 1 : 0;
;         if (lane == 0) s_flag[PAR * 4 + w] = wd;
;         __syncthreads();
;         const int f0 = s_flag[PAR * 4 + 0], f1 = s_flag[PAR * 4 + 1], f2 = s_flag[PAR * 4 + 2], f3 = s_flag[PAR * 4 + 3];
;         if (f0 & f1 & f2 & f3) return true;
;       } else {
;         __syncthreads();
;       }
;       constexpr int buf = PAR;
;       if (MODE == 2) { const float fl = aa.Fh[(size_t)bh * LP + (kt > 0 ? kt * 64 - 1 : 0)]; __builtin_amdgcn_sched_barrier(0); nfnext = (kt > 0) ? -fl * LOG2E : 0.f; }
;       { const int kpre = kt > 1 ? kt - 2 : 0; if (PAR == 0) gload(rkA, rvA, rfA, kpre); else gload(rkB, rvB, rfB, kpre); }
;       if (kt * 64 <= wqmax && dry < 2) {
;         const bf16_t* Kb = Kl + buf * 64 * KST; const bf16_t* Vb = Vl + buf * 64 * VST;
;         f32x16 s[2];
; #pragma unroll
;         for (int i = 0; i < 16; ++i) { s[0][i] = 0.f; s[1][i] = 0.f; }
;         if (MODE == 0) {
; #pragma unroll
;           for (int ks = 0; ks < NKS; ++ks) {
;             const bf16x8 a0 = *(const bf16x8*)(Kb + r * KST + ks * 16 + 8 * hh);
;             const bf16x8 a1 = *(const bf16x8*)(Kb + (32 + r) * KST + ks * 16 + 8 * hh);
;             s[0] = MFMA32(a0, qf[ks], s[0]);
;             s[1] = MFMA32(a1, qf[ks], s[1]);
;           }
;         } else {
;           bf16x8 kf0[NKS], kf1[NKS];
; #pragma unroll
;           for (int ks = 0; ks < NKS; ++ks) kf0[ks] = *(const bf16x8*)(Kb + r * KST + ks * 16 + 8 * hh);
; #pragma unroll
;           for (int ks = 0; ks < NKS; ++ks) kf1[ks] = *(const bf16x8*)(Kb + (32 + r) * KST + ks * 16 + 8 * hh);
;           __builtin_amdgcn_sched_barrier(0);
; #pragma unroll
;           for (int ks = 0; ks < NKS; ++ks) s[0] = MFMA32(kf0[ks], qf[ks], s[0]);
; #pragma unroll
;           for (int ks = 0; ks < NKS; ++ks) s[1] = MFMA32(kf1[ks], qf[ks], s[1]);
;           __builtin_amdgcn_sched_barrier(0);
;         }
;         const int kbase = kt * 64 + 4 * hh;
;         u32x4 vfr[2][2];
;         auto ldv = [&](int j) {
; #pragma unroll
;           for (int st = 0; st < 2; ++st)
; #pragma unroll
;             for (int dt = 0; dt < 2; ++dt) {
;               const bf16_t* vp = Vb + (dt * 32 + r) * VST + j * 32 + 16 * st + 4 * hh;
.LBB0_420:
	v_pk_add_f32 v[32:33], v[150:151], v[156:157]
	s_nop 0
	v_cmp_lt_f32_e32 vcc, v32, v33
	s_or_b64 s[4:5], s[50:51], vcc
	v_cndmask_b32_e64 v32, 0, 1, s[4:5]
	v_cmp_ne_u32_e32 vcc, 0, v32
	s_mov_b64 s[4:5], exec
	s_and_saveexec_b64 s[8:9], s[46:47]
	s_cmp_eq_u64 vcc, s[4:5]
	s_cselect_b64 s[4:5], -1, 0
	v_cndmask_b32_e64 v32, 0, 1, s[4:5]
	ds_write_b32 v164, v32 offset:36384
	s_or_b64 exec, exec, s[8:9]
	s_waitcnt lgkmcnt(0)
	s_barrier
	ds_read_b128 v[32:35], v145 offset:36384
	s_mov_b64 s[4:5], -1
	s_waitcnt lgkmcnt(0)
	v_and_b32_e32 v32, v33, v32
	v_and_b32_e32 v32, v32, v34
	v_and_b32_e32 v32, v32, v35
	v_cmp_ne_u32_e32 vcc, 0, v32
	s_cbranch_vccnz .LBB0_400
	s_lshl_b32 s1, s11, 6
	s_add_i32 s8, s1, -1
	s_cmp_gt_i32 s11, 0
	s_cselect_b64 s[52:53], -1, 0
	s_and_b64 s[4:5], s[52:53], exec
	s_cselect_b32 s18, s8, 0
	s_lshl_b64 s[4:5], s[18:19], 2
	s_add_u32 s4, s6, s4
	s_addc_u32 s5, s7, s5
	global_load_dword v156, v145, s[4:5]
	s_max_i32 s4, s11, 2
	s_lshl_b32 s4, s4, 6
	s_addk_i32 s4, 0xff80
	v_add_u32_e32 v32, s4, v129
	v_min_i32_e32 v32, 0x200f, v32
	v_add_u32_e32 v32, s10, v32
	v_ashrrev_i32_e32 v33, 31, v32
	v_lshlrev_b64 v[32:33], 11, v[32:33]
	v_lshl_add_u64 v[32:33], v[152:153], 0, v[32:33]
	global_load_dwordx4 v[96:99], v[32:33], off
	global_load_dwordx4 v[100:103], v[32:33], off offset:64
	s_ashr_i32 s5, s4, 31
	v_lshl_add_u64 v[32:33], s[4:5], 1, v[142:143]
	global_load_dwordx4 v[104:107], v[32:33], off
	global_load_dwordx4 v[108:111], v[32:33], off offset:64
	v_lshl_add_u64 v[32:33], s[4:5], 2, v[154:155]
	global_load_dword v188, v[32:33], off
	v_cmp_le_i32_e32 vcc, s1, v189
	s_and_saveexec_b64 s[4:5], vcc
	s_cbranch_execz .LBB0_435
	ds_read_b128 v[32:35], v166 offset:9216
	ds_read_b128 v[36:39], v166 offset:9248
	ds_read_b128 v[40:43], v166 offset:9280
	ds_read_b128 v[44:47], v166 offset:9312
	ds_read_b128 v[112:115], v166 offset:13824
	ds_read_b128 v[116:119], v166 offset:13856
	ds_read_b128 v[120:123], v166 offset:13888
	ds_read_b128 v[124:127], v166 offset:13920
	s_waitcnt lgkmcnt(7)
	v_mfma_f32_32x32x16_bf16 v[48:63], v[32:35], v[64:67], 0
	s_waitcnt lgkmcnt(6)
	v_mfma_f32_32x32x16_bf16 v[48:63], v[36:39], v[68:71], v[48:63]
	s_waitcnt lgkmcnt(5)
	v_mfma_f32_32x32x16_bf16 v[48:63], v[40:43], v[72:75], v[48:63]
	s_waitcnt lgkmcnt(4)
	v_mfma_f32_32x32x16_bf16 v[48:63], v[44:47], v[76:79], v[48:63]
	s_waitcnt lgkmcnt(3)
	v_mfma_f32_32x32x16_bf16 v[32:47], v[112:115], v[64:67], 0
	s_waitcnt lgkmcnt(2)
	v_mfma_f32_32x32x16_bf16 v[32:47], v[116:119], v[68:71], v[32:47]
	s_waitcnt lgkmcnt(1)
	v_mfma_f32_32x32x16_bf16 v[32:47], v[120:123], v[72:75], v[32:47]
	s_waitcnt lgkmcnt(0)
	v_mfma_f32_32x32x16_bf16 v[32:47], v[124:127], v[76:79], v[32:47]
	v_subrev_u32_e32 v112, s1, v167
	v_add_u32_e32 v194, 0x6800, v168
	v_add_u32_e32 v195, 0x7800, v168
	v_add_u32_e32 v192, v112, v139
	ds_read_b128 v[124:127], v168 offset:36864
	ds_read_b128 v[112:115], v168 offset:36896
	ds_read_b128 v[120:123], v168 offset:41472
	ds_read_b128 v[116:119], v168 offset:41504
	v_cmp_gt_i32_e64 s[54:55], s1, v190
	ds_read_b128 v[196:199], v165 offset:36096
	ds_read_b128 v[200:203], v165 offset:36128
	s_waitcnt lgkmcnt(1)
	v_pk_fma_f32 v[160:161], v[48:49], s[36:37], v[196:197] op_sel_hi:[1,0,1]
	v_pk_fma_f32 v[158:159], v[50:51], s[36:37], v[198:199] op_sel_hi:[1,0,1]
	ds_read_b128 v[196:199], v165 offset:36160
	s_waitcnt lgkmcnt(1)
	v_pk_fma_f32 v[50:51], v[52:53], s[36:37], v[200:201] op_sel_hi:[1,0,1]
	v_pk_fma_f32 v[48:49], v[54:55], s[36:37], v[202:203] op_sel_hi:[1,0,1]
	s_waitcnt lgkmcnt(0)
	v_pk_fma_f32 v[54:55], v[56:57], s[36:37], v[196:197] op_sel_hi:[1,0,1]
	v_pk_fma_f32 v[52:53], v[58:59], s[36:37], v[198:199] op_sel_hi:[1,0,1]
	ds_read_b128 v[56:59], v165 offset:36192
	s_waitcnt lgkmcnt(0)
	v_pk_fma_f32 v[56:57], v[60:61], s[36:37], v[56:57] op_sel_hi:[1,0,1]
	v_pk_fma_f32 v[58:59], v[62:63], s[36:37], v[58:59] op_sel_hi:[1,0,1]
	s_and_saveexec_b64 s[8:9], s[54:55]
	s_cbranch_execz .LBB0_426
	v_cmp_lt_i32_e32 vcc, -1, v192
	s_nop 1
	v_cndmask_b32_e32 v160, v185, v160, vcc
	v_cmp_lt_i32_e32 vcc, 0, v192
	s_nop 1
	v_cndmask_b32_e32 v161, v185, v161, vcc
	v_cmp_lt_i32_e32 vcc, 1, v192
	s_nop 1
	v_cndmask_b32_e32 v158, v185, v158, vcc
	v_cmp_lt_i32_e32 vcc, 2, v192
	s_nop 1
	v_cndmask_b32_e32 v159, v185, v159, vcc
	v_cmp_lt_i32_e32 vcc, 7, v192
	s_nop 1
	v_cndmask_b32_e32 v50, v185, v50, vcc
	v_cmp_lt_i32_e32 vcc, 8, v192
	s_nop 1
	v_cndmask_b32_e32 v51, v185, v51, vcc
	v_cmp_lt_i32_e32 vcc, 9, v192
	s_nop 1
	v_cndmask_b32_e32 v48, v185, v48, vcc
	v_cmp_lt_i32_e32 vcc, 10, v192
	s_nop 1
	v_cndmask_b32_e32 v49, v185, v49, vcc
	v_cmp_lt_i32_e32 vcc, 15, v192
	s_nop 1
	v_cndmask_b32_e32 v54, v185, v54, vcc
	v_cmp_lt_i32_e32 vcc, 16, v192
	s_nop 1
	v_cndmask_b32_e32 v55, v185, v55, vcc
	v_cmp_lt_i32_e32 vcc, 17, v192
	s_nop 1
	v_cndmask_b32_e32 v52, v185, v52, vcc
	v_cmp_lt_i32_e32 vcc, 18, v192
	s_nop 1
	v_cndmask_b32_e32 v53, v185, v53, vcc
	v_cmp_lt_i32_e32 vcc, 23, v192
	s_nop 1
	v_cndmask_b32_e32 v56, v185, v56, vcc
	v_cmp_lt_i32_e32 vcc, 24, v192
	s_nop 1
	v_cndmask_b32_e32 v57, v185, v57, vcc
	v_cmp_lt_i32_e32 vcc, 25, v192
	s_nop 1
	v_cndmask_b32_e32 v58, v185, v58, vcc
	v_cmp_lt_i32_e32 vcc, 26, v192
	s_nop 1
	v_cndmask_b32_e32 v59, v185, v59, vcc

; DI float fexp2(float x) { return __builtin_amdgcn_exp2f(x); }
;     ...
;           for (int j = 0; j < 2; ++j) {
;             ldv(j);
;             if (MODE == 2) {
; #pragma unroll
;               for (int g = 0; g < 4; ++g) {
;                 const f32x4 nf = *(const f32x4*)(Fl + buf * 64 + j * 32 + 8 * g + 4 * hh);
; #pragma unroll
;                 for (int e = 0; e < 4; ++e) s[j][4 * g + e] = fmaf(s[j][4 * g + e], c2, nf[e]);
;               }
;             }
;             if (diag) {
;               asm volatile("" ::: "memory");
; #pragma unroll
;               for (int i = 0; i < 16; ++i) s[j][i] = (j * 32 + 8 * (i >> 2) + (i & 3)) <= dq ? s[j][i] : -INFINITY;
;             }
;             float mt = fmaxf(s[j][0], s[j][1]);
; #pragma unroll
;             for (int i = 2; i < 16; ++i) mt = fmaxf(mt, s[j][i]);
;             mt = fmaxf(mt, __shfl_xor(mt, 32));
;             if (MODE == 1) mt *= c2;
;             const float cand = fmaxf(mrun, mt);
;             if (__any(cand > mrun + 8.f)) {
;               const float alpha = fexp2(mrun - cand);
;               mrun = cand; lsum *= alpha;
; #pragma unroll
;               for (int i = 0; i < 16; ++i) { oacc[0][i] *= alpha; oacc[1][i] *= alpha; }
;             }
;             const float nm = -mrun;
; #pragma unroll
;             for (int i = 0; i < 16; ++i) {
;               const float p = (MODE == 1) ? fexp2(fmaf(s[j][i], c2, nm)) : fexp2(s[j][i] + nm);
;               lsum += p; s[j][i] = p;
;             }
;             pvm(j);
.LBB0_429:
	v_sub_f32_e32 v48, v48, v193
	v_exp_f32_e32 v201, v48
	v_sub_f32_e32 v48, v49, v193
	v_sub_f32_e32 v60, v160, v193
	v_exp_f32_e32 v202, v48
	v_sub_f32_e32 v48, v54, v193
	v_exp_f32_e32 v160, v60
	v_sub_f32_e32 v60, v161, v193
	v_exp_f32_e32 v203, v48
	v_sub_f32_e32 v48, v55, v193
	v_exp_f32_e32 v196, v60
	v_sub_f32_e32 v60, v158, v193
	v_sub_f32_e32 v50, v50, v193
	v_exp_f32_e32 v204, v48
	v_sub_f32_e32 v48, v52, v193
	v_exp_f32_e32 v197, v60
	v_sub_f32_e32 v60, v159, v193
	v_exp_f32_e32 v199, v50
	v_sub_f32_e32 v50, v51, v193
	v_exp_f32_e32 v205, v48
	v_sub_f32_e32 v48, v53, v193
	v_exp_f32_e32 v198, v60
	v_exp_f32_e32 v200, v50
	v_exp_f32_e32 v206, v48
	v_sub_f32_e32 v48, v56, v193
	v_exp_f32_e32 v157, v48
	v_sub_f32_e32 v48, v57, v193
	v_exp_f32_e32 v158, v48
	v_sub_f32_e32 v48, v58, v193
	v_exp_f32_e32 v159, v48
	v_sub_f32_e32 v48, v59, v193
	v_exp_f32_e32 v161, v48
	v_cvt_pk_bf16_f32 v48, v160, v196
	v_cvt_pk_bf16_f32 v49, v197, v198
	v_cvt_pk_bf16_f32 v50, v199, v200
	v_cvt_pk_bf16_f32 v51, v201, v202
	s_nop 1
	v_mfma_f32_32x32x16_bf16 v[16:31], v[124:127], v[48:51], v[16:31]
	v_mfma_f32_32x32x16_bf16 v[0:15], v[120:123], v[48:51], v[0:15]
	v_cvt_pk_bf16_f32 v48, v203, v204
	v_cvt_pk_bf16_f32 v49, v205, v206
	v_cvt_pk_bf16_f32 v50, v157, v158
	v_cvt_pk_bf16_f32 v51, v159, v161
	s_nop 1
	v_mfma_f32_32x32x16_bf16 v[16:31], v[112:115], v[48:51], v[16:31]
	v_mfma_f32_32x32x16_bf16 v[0:15], v[116:119], v[48:51], v[0:15]
	ds_read_b128 v[60:63], v168 offset:36928
	ds_read_b128 v[52:55], v168 offset:36960
	ds_read_b128 v[56:59], v168 offset:41536
	ds_read_b128 v[48:51], v168 offset:41568
	ds_read_b128 v[114:117], v165 offset:36224
	ds_read_b128 v[118:121], v165 offset:36256
	s_waitcnt lgkmcnt(1)
	v_pk_fma_f32 v[112:113], v[34:35], s[36:37], v[116:117] op_sel_hi:[1,0,1]
	s_waitcnt lgkmcnt(0)
	v_pk_fma_f32 v[36:37], v[36:37], s[36:37], v[118:119] op_sel_hi:[1,0,1]
	ds_read_b128 v[116:119], v165 offset:36288
	v_pk_fma_f32 v[114:115], v[32:33], s[36:37], v[114:115] op_sel_hi:[1,0,1]
	v_pk_fma_f32 v[34:35], v[38:39], s[36:37], v[120:121] op_sel_hi:[1,0,1]
	s_waitcnt lgkmcnt(0)
	v_pk_fma_f32 v[40:41], v[40:41], s[36:37], v[116:117] op_sel_hi:[1,0,1]
	v_pk_fma_f32 v[32:33], v[42:43], s[36:37], v[118:119] op_sel_hi:[1,0,1]
	ds_read_b128 v[116:119], v165 offset:36320
	s_waitcnt lgkmcnt(0)
	v_pk_fma_f32 v[42:43], v[44:45], s[36:37], v[116:117] op_sel_hi:[1,0,1]
	v_pk_fma_f32 v[38:39], v[46:47], s[36:37], v[118:119] op_sel_hi:[1,0,1]
	s_and_saveexec_b64 s[8:9], s[54:55]
	s_cbranch_execz .LBB0_431
	v_cmp_lt_i32_e32 vcc, 31, v192
	s_nop 1
	v_cndmask_b32_e32 v114, v185, v114, vcc
	v_cmp_lt_i32_e32 vcc, 32, v192
	s_nop 1
	v_cndmask_b32_e32 v115, v185, v115, vcc
	v_cmp_lt_i32_e32 vcc, 33, v192
	s_nop 1
	v_cndmask_b32_e32 v112, v185, v112, vcc
	v_cmp_lt_i32_e32 vcc, 34, v192
	s_nop 1
	v_cndmask_b32_e32 v113, v185, v113, vcc
	v_cmp_lt_i32_e32 vcc, 39, v192
	s_nop 1
	v_cndmask_b32_e32 v36, v185, v36, vcc
	v_cmp_lt_i32_e32 vcc, 40, v192
	s_nop 1
	v_cndmask_b32_e32 v37, v185, v37, vcc
	v_cmp_lt_i32_e32 vcc, 41, v192
	s_nop 1
	v_cndmask_b32_e32 v34, v185, v34, vcc
	v_cmp_lt_i32_e32 vcc, 42, v192
	s_nop 1
	v_cndmask_b32_e32 v35, v185, v35, vcc
	v_cmp_lt_i32_e32 vcc, 47, v192
	s_nop 1
	v_cndmask_b32_e32 v40, v185, v40, vcc
	v_cmp_lt_i32_e32 vcc, 48, v192
	s_nop 1
	v_cndmask_b32_e32 v41, v185, v41, vcc
	v_cmp_lt_i32_e32 vcc, 49, v192
	s_nop 1
	v_cndmask_b32_e32 v32, v185, v32, vcc
	v_cmp_lt_i32_e32 vcc, 50, v192
	s_nop 1
	v_cndmask_b32_e32 v33, v185, v33, vcc
	v_cmp_lt_i32_e32 vcc, 55, v192
	s_nop 1
	v_cndmask_b32_e32 v42, v185, v42, vcc
	v_cmp_lt_i32_e32 vcc, 56, v192
	s_nop 1
	v_cndmask_b32_e32 v43, v185, v43, vcc
	v_cmp_lt_i32_e32 vcc, 57, v192
	s_nop 1
	v_cndmask_b32_e32 v38, v185, v38, vcc
	v_cmp_lt_i32_e32 vcc, 58, v192
	s_nop 1
	v_cndmask_b32_e32 v39, v185, v39, vcc

;     ...
;     auto lstore = [&](const u32x4 (&rk)[KCH], const u32x4 (&rv)[2], const float rf, int buf) {
;       bf16_t* kd = Kl + buf * 64 * KST + lkey * KST + lsub * 8;
;       *(u32x4*)kd = rk[0]; *(u32x4*)(kd + 32) = rk[1];
;       if (MODE == 1) *(u32x4*)(kd + 64) = rk[KCH - 1];
;       bf16_t* vd = Vl + buf * 64 * VST + lkey * VST + lsub * 8;
;       u32x2 lo, hi;
;       lo[0] = rv[0][0]; lo[1] = rv[0][1]; hi[0] = rv[0][2]; hi[1] = rv[0][3];
;       *(u32x2*)vd = lo; *(u32x2*)(vd + 4) = hi;
;       lo[0] = rv[1][0]; lo[1] = rv[1][1]; hi[0] = rv[1][2]; hi[1] = rv[1][3];
;       *(u32x2*)(vd + 32) = lo; *(u32x2*)(vd + 36) = hi;
;       if (MODE == 2 && t < 64) Fl[buf * 64 + t] = -rf * LOG2E;
;     };
.LBB0_435:
	s_or_b64 exec, exec, s[4:5]
	s_waitcnt vmcnt(10)
	ds_write_b128 v130, v[80:83]
	s_waitcnt vmcnt(9)
	ds_write_b128 v130, v[84:87] offset:64
	s_waitcnt vmcnt(8)
	ds_write2_b64 v137, v[88:89], v[90:91] offset1:2
	s_waitcnt vmcnt(7)
	ds_write2_b64 v171, v[92:93], v[94:95] offset1:2
	s_and_saveexec_b64 s[4:5], s[44:45]
	s_cbranch_execz .LBB0_437
	s_waitcnt vmcnt(6)
	v_mul_f32_e32 v32, 0xbfb8aa3b, v187
	ds_write_b32 v163, v32 offset:35840
